# GEMM k-loop counted vmcnt waits; PEER top-k: med3 sorted insertion with hoisted key loads, ballot bit-search threshold instead of 50-way rank count
# speedup vs baseline: 1.0151x; 1.0151x over previous
.LBB0_302:
	ds_read_b128 v[188:191], v136
	ds_read_b128 v[192:195], v136 offset:4608
	ds_read_b128 v[196:199], v137 offset:36864
	ds_read_b128 v[214:217], v137 offset:41472
	ds_read_b128 v[218:221], v136 offset:32
	ds_read_b128 v[222:225], v136 offset:4640
	ds_read_b128 v[226:229], v137 offset:36896
	ds_read_b128 v[230:233], v137 offset:41504
	s_waitcnt lgkmcnt(5)
	v_mfma_f32_32x32x16_bf16 v[50:65], v[188:191], v[196:199], v[50:65]
	s_waitcnt lgkmcnt(4)
	v_mfma_f32_32x32x16_bf16 v[34:49], v[188:191], v[214:217], v[34:49]
	v_mfma_f32_32x32x16_bf16 v[18:33], v[192:195], v[196:199], v[18:33]
	v_mfma_f32_32x32x16_bf16 v[2:17], v[192:195], v[214:217], v[2:17]
	ds_read_b128 v[188:191], v136 offset:64
	ds_read_b128 v[192:195], v136 offset:4672
	ds_read_b128 v[196:199], v137 offset:36928
	ds_read_b128 v[214:217], v137 offset:41536
	s_waitcnt lgkmcnt(5)
	v_mfma_f32_32x32x16_bf16 v[50:65], v[218:221], v[226:229], v[50:65]
	s_waitcnt lgkmcnt(4)
	v_mfma_f32_32x32x16_bf16 v[34:49], v[218:221], v[230:233], v[34:49]
	v_mfma_f32_32x32x16_bf16 v[18:33], v[222:225], v[226:229], v[18:33]
	v_mfma_f32_32x32x16_bf16 v[2:17], v[222:225], v[230:233], v[2:17]
	ds_read_b128 v[218:221], v136 offset:96
	ds_read_b128 v[222:225], v136 offset:4704
	ds_read_b128 v[226:229], v137 offset:36960
	ds_read_b128 v[230:233], v137 offset:41568
	s_waitcnt lgkmcnt(5)
	v_mfma_f32_32x32x16_bf16 v[50:65], v[188:191], v[196:199], v[50:65]
	s_waitcnt lgkmcnt(4)
	v_mfma_f32_32x32x16_bf16 v[34:49], v[188:191], v[214:217], v[34:49]
	v_mfma_f32_32x32x16_bf16 v[18:33], v[192:195], v[196:199], v[18:33]
	v_mfma_f32_32x32x16_bf16 v[2:17], v[192:195], v[214:217], v[2:17]
	s_waitcnt lgkmcnt(1)
	v_mfma_f32_32x32x16_bf16 v[50:65], v[218:221], v[226:229], v[50:65]
	s_waitcnt lgkmcnt(0)
	v_mfma_f32_32x32x16_bf16 v[34:49], v[218:221], v[230:233], v[34:49]
	v_mfma_f32_32x32x16_bf16 v[18:33], v[222:225], v[226:229], v[18:33]
	v_mfma_f32_32x32x16_bf16 v[2:17], v[222:225], v[230:233], v[2:17]
	s_cmp_gt_u32 s4, 13
	s_cbranch_scc1 .Lg1_last_half
	s_waitcnt vmcnt(11)
	ds_write_b128 v182, v[102:105] offset:18432
	ds_write_b128 v182, v[98:101] offset:55296
	s_waitcnt vmcnt(10)
	ds_write_b128 v182, v[110:113] offset:23040
	ds_write_b128 v182, v[106:109] offset:59904
	s_waitcnt vmcnt(9)
	ds_write_b128 v182, v[118:121] offset:27648
	ds_write_b128 v182, v[114:117] offset:64512
	s_waitcnt vmcnt(8)
	ds_write_b128 v182, v[126:129] offset:32256
	ds_write_b128 v184, v[122:125] offset:13824
	s_branch .Lg1_stored
.Lg1_last_half:
	s_waitcnt vmcnt(3)
	ds_write_b128 v182, v[102:105] offset:18432
	ds_write_b128 v182, v[98:101] offset:55296
	s_waitcnt vmcnt(2)
	ds_write_b128 v182, v[110:113] offset:23040
	ds_write_b128 v182, v[106:109] offset:59904
	s_waitcnt vmcnt(1)
	ds_write_b128 v182, v[118:121] offset:27648
	ds_write_b128 v182, v[114:117] offset:64512
	s_waitcnt vmcnt(0)
	ds_write_b128 v182, v[126:129] offset:32256
	ds_write_b128 v184, v[122:125] offset:13824
.Lg1_stored:
	s_cmp_gt_u32 s4, 12
	s_waitcnt lgkmcnt(0)
	s_barrier
	s_cbranch_scc1 .LBB0_304
	v_add_co_u32_e32 v102, vcc, 0x13800000, v176
	v_lshl_add_u64 v[98:99], v[164:165], 0, v[138:139]
	s_nop 0
	v_addc_co_u32_e32 v103, vcc, 0, v177, vcc
	v_add_co_u32_e32 v106, vcc, 0x13810000, v176
	global_load_dwordx4 v[98:101], v[98:99], off
	s_nop 0
	v_addc_co_u32_e32 v107, vcc, 0, v177, vcc
	v_add_co_u32_e32 v118, vcc, 0x13820000, v176
	global_load_dwordx4 v[102:105], v[102:103], off offset:384
	s_nop 0
	global_load_dwordx4 v[110:113], v[106:107], off offset:384
	v_addc_co_u32_e32 v119, vcc, 0, v177, vcc
	v_add_co_u32_e32 v122, vcc, 0x13830000, v176
	v_lshl_add_u64 v[106:107], v[162:163], 0, v[138:139]
	s_nop 0
	v_addc_co_u32_e32 v123, vcc, 0, v177, vcc
	global_load_dwordx4 v[106:109], v[106:107], off
	s_nop 0
	global_load_dwordx4 v[114:117], v[178:179], off offset:128
	s_nop 0
	global_load_dwordx4 v[118:121], v[118:119], off offset:384
	s_nop 0
	global_load_dwordx4 v[126:129], v[122:123], off offset:384
	s_nop 0
	global_load_dwordx4 v[122:125], v[174:175], off
.LBB0_304:
	ds_read_b128 v[174:177], v136 offset:18432
	ds_read_b128 v[188:191], v136 offset:23040
	ds_read_b128 v[192:195], v137 offset:55296
	ds_read_b128 v[196:199], v137 offset:59904
	ds_read_b128 v[214:217], v136 offset:18464
	ds_read_b128 v[218:221], v136 offset:23072
	ds_read_b128 v[222:225], v137 offset:55328
	ds_read_b128 v[226:229], v137 offset:59936
	s_waitcnt lgkmcnt(5)
	v_mfma_f32_32x32x16_bf16 v[50:65], v[174:177], v[192:195], v[50:65]
	s_waitcnt lgkmcnt(4)
	v_mfma_f32_32x32x16_bf16 v[34:49], v[174:177], v[196:199], v[34:49]
	v_mfma_f32_32x32x16_bf16 v[18:33], v[188:191], v[192:195], v[18:33]
	v_mfma_f32_32x32x16_bf16 v[2:17], v[188:191], v[196:199], v[2:17]
	ds_read_b128 v[174:177], v136 offset:18496
	ds_read_b128 v[188:191], v136 offset:23104
	ds_read_b128 v[192:195], v137 offset:55360
	ds_read_b128 v[196:199], v137 offset:59968
	s_waitcnt lgkmcnt(5)
	v_mfma_f32_32x32x16_bf16 v[50:65], v[214:217], v[222:225], v[50:65]
	s_waitcnt lgkmcnt(4)
	v_mfma_f32_32x32x16_bf16 v[34:49], v[214:217], v[226:229], v[34:49]
	v_mfma_f32_32x32x16_bf16 v[18:33], v[218:221], v[222:225], v[18:33]
	v_mfma_f32_32x32x16_bf16 v[2:17], v[218:221], v[226:229], v[2:17]
	ds_read_b128 v[214:217], v136 offset:18528
	ds_read_b128 v[218:221], v136 offset:23136
	ds_read_b128 v[222:225], v137 offset:55392
	ds_read_b128 v[226:229], v137 offset:60000
	s_waitcnt lgkmcnt(5)
	v_mfma_f32_32x32x16_bf16 v[50:65], v[174:177], v[192:195], v[50:65]
	s_waitcnt lgkmcnt(4)
	v_mfma_f32_32x32x16_bf16 v[34:49], v[174:177], v[196:199], v[34:49]
	v_mfma_f32_32x32x16_bf16 v[18:33], v[188:191], v[192:195], v[18:33]
	v_mfma_f32_32x32x16_bf16 v[2:17], v[188:191], v[196:199], v[2:17]
	s_waitcnt lgkmcnt(1)
	v_mfma_f32_32x32x16_bf16 v[50:65], v[214:217], v[222:225], v[50:65]
	s_waitcnt lgkmcnt(0)
	v_mfma_f32_32x32x16_bf16 v[34:49], v[214:217], v[226:229], v[34:49]
	v_mfma_f32_32x32x16_bf16 v[18:33], v[218:221], v[222:225], v[18:33]
	v_mfma_f32_32x32x16_bf16 v[2:17], v[218:221], v[226:229], v[2:17]
	s_andn2_b64 vcc, exec, s[2:3]
	s_cbranch_vccnz .LBB0_299
	s_waitcnt vmcnt(14)
	ds_write_b128 v182, v[70:73]
	ds_write_b128 v182, v[66:69] offset:36864
	s_waitcnt vmcnt(12)
	ds_write_b128 v182, v[74:77] offset:4608
	ds_write_b128 v182, v[78:81] offset:41472
	s_waitcnt vmcnt(10)
	ds_write_b128 v182, v[86:89] offset:9216
	ds_write_b128 v182, v[82:85] offset:46080
	s_waitcnt vmcnt(8)
	ds_write_b128 v182, v[94:97] offset:13824
	ds_write_b128 v182, v[90:93] offset:50688
	s_branch .LBB0_299

.LBB0_635:
	ds_read_b128 v[152:155], v134
	ds_read_b128 v[156:159], v134 offset:4608
	ds_read_b128 v[162:165], v148 offset:36864
	ds_read_b128 v[166:169], v148 offset:41472
	ds_read_b128 v[170:173], v134 offset:32
	ds_read_b128 v[174:177], v134 offset:4640
	ds_read_b128 v[178:181], v148 offset:36896
	ds_read_b128 v[182:185], v148 offset:41504
	s_waitcnt lgkmcnt(5)
	v_mfma_f32_32x32x16_bf16 v[50:65], v[152:155], v[162:165], v[50:65]
	s_waitcnt lgkmcnt(4)
	v_mfma_f32_32x32x16_bf16 v[34:49], v[152:155], v[166:169], v[34:49]
	v_mfma_f32_32x32x16_bf16 v[18:33], v[156:159], v[162:165], v[18:33]
	v_mfma_f32_32x32x16_bf16 v[2:17], v[156:159], v[166:169], v[2:17]
	ds_read_b128 v[152:155], v134 offset:64
	ds_read_b128 v[156:159], v134 offset:4672
	ds_read_b128 v[162:165], v148 offset:36928
	ds_read_b128 v[166:169], v148 offset:41536
	s_waitcnt lgkmcnt(5)
	v_mfma_f32_32x32x16_bf16 v[50:65], v[170:173], v[178:181], v[50:65]
	s_waitcnt lgkmcnt(4)
	v_mfma_f32_32x32x16_bf16 v[34:49], v[170:173], v[182:185], v[34:49]
	v_mfma_f32_32x32x16_bf16 v[18:33], v[174:177], v[178:181], v[18:33]
	v_mfma_f32_32x32x16_bf16 v[2:17], v[174:177], v[182:185], v[2:17]
	ds_read_b128 v[170:173], v134 offset:96
	ds_read_b128 v[174:177], v134 offset:4704
	ds_read_b128 v[178:181], v148 offset:36960
	ds_read_b128 v[182:185], v148 offset:41568
	s_waitcnt lgkmcnt(5)
	v_mfma_f32_32x32x16_bf16 v[50:65], v[152:155], v[162:165], v[50:65]
	s_waitcnt lgkmcnt(4)
	v_mfma_f32_32x32x16_bf16 v[34:49], v[152:155], v[166:169], v[34:49]
	v_mfma_f32_32x32x16_bf16 v[18:33], v[156:159], v[162:165], v[18:33]
	v_mfma_f32_32x32x16_bf16 v[2:17], v[156:159], v[166:169], v[2:17]
	s_waitcnt lgkmcnt(1)
	v_mfma_f32_32x32x16_bf16 v[50:65], v[170:173], v[178:181], v[50:65]
	s_waitcnt lgkmcnt(0)
	v_mfma_f32_32x32x16_bf16 v[34:49], v[170:173], v[182:185], v[34:49]
	v_mfma_f32_32x32x16_bf16 v[18:33], v[174:177], v[178:181], v[18:33]
	v_mfma_f32_32x32x16_bf16 v[2:17], v[174:177], v[182:185], v[2:17]
	s_cmp_gt_u32 s5, 13
	s_cbranch_scc1 .Lg2_last_half
	s_waitcnt vmcnt(11)
	ds_write_b128 v146, v[82:85] offset:18432
	ds_write_b128 v146, v[86:89] offset:55296
	s_waitcnt vmcnt(10)
	ds_write_b128 v146, v[94:97] offset:23040
	ds_write_b128 v146, v[98:101] offset:59904
	s_waitcnt vmcnt(9)
	ds_write_b128 v146, v[106:109] offset:27648
	ds_write_b128 v146, v[110:113] offset:64512
	s_waitcnt vmcnt(8)
	ds_write_b128 v146, v[122:125] offset:32256
	ds_write_b128 v149, v[126:129] offset:13824
	s_branch .Lg2_stored
.Lg2_last_half:
	s_waitcnt vmcnt(3)
	ds_write_b128 v146, v[82:85] offset:18432
	ds_write_b128 v146, v[86:89] offset:55296
	s_waitcnt vmcnt(2)
	ds_write_b128 v146, v[94:97] offset:23040
	ds_write_b128 v146, v[98:101] offset:59904
	s_waitcnt vmcnt(1)
	ds_write_b128 v146, v[106:109] offset:27648
	ds_write_b128 v146, v[110:113] offset:64512
	s_waitcnt vmcnt(0)
	ds_write_b128 v146, v[122:125] offset:32256
	ds_write_b128 v149, v[126:129] offset:13824
.Lg2_stored:
	s_cmp_gt_u32 s5, 12
	s_waitcnt lgkmcnt(0)
	s_barrier
	s_cbranch_scc1 .LBB0_637
	v_add_co_u32_e32 v82, vcc, 0x15c00000, v144
	s_nop 1
	v_addc_co_u32_e32 v83, vcc, 0, v145, vcc
	v_add_co_u32_e32 v86, vcc, 0x1000000, v142
	global_load_dwordx4 v[82:85], v[82:83], off offset:384
	s_nop 0
	v_addc_co_u32_e32 v87, vcc, 0, v143, vcc
	v_add_co_u32_e32 v94, vcc, 0x15c10000, v144
	global_load_dwordx4 v[86:89], v[86:87], off offset:384
	s_nop 0
	v_addc_co_u32_e32 v95, vcc, 0, v145, vcc
	v_add_co_u32_e32 v98, vcc, 0x1010000, v142
	global_load_dwordx4 v[94:97], v[94:95], off offset:384
	s_nop 0
	v_addc_co_u32_e32 v99, vcc, 0, v143, vcc
	v_add_co_u32_e32 v106, vcc, 0x15c20000, v144
	global_load_dwordx4 v[98:101], v[98:99], off offset:384
	s_nop 0
	v_addc_co_u32_e32 v107, vcc, 0, v145, vcc
	v_add_co_u32_e32 v110, vcc, 0x1020000, v142
	global_load_dwordx4 v[106:109], v[106:107], off offset:384
	s_nop 0
	v_addc_co_u32_e32 v111, vcc, 0, v143, vcc
	v_add_co_u32_e32 v122, vcc, 0x15c30000, v144
	global_load_dwordx4 v[110:113], v[110:111], off offset:384
	s_nop 0
	v_addc_co_u32_e32 v123, vcc, 0, v145, vcc
	v_add_co_u32_e32 v126, vcc, 0x1030000, v142
	global_load_dwordx4 v[122:125], v[122:123], off offset:384
	s_nop 0
	v_addc_co_u32_e32 v127, vcc, 0, v143, vcc
	global_load_dwordx4 v[126:129], v[126:127], off offset:384
.LBB0_637:
	ds_read_b128 v[142:145], v134 offset:18432
	ds_read_b128 v[152:155], v134 offset:23040
	ds_read_b128 v[156:159], v148 offset:55296
	ds_read_b128 v[162:165], v148 offset:59904
	ds_read_b128 v[166:169], v134 offset:18464
	ds_read_b128 v[170:173], v134 offset:23072
	ds_read_b128 v[174:177], v148 offset:55328
	ds_read_b128 v[178:181], v148 offset:59936
	s_waitcnt lgkmcnt(5)
	v_mfma_f32_32x32x16_bf16 v[50:65], v[142:145], v[156:159], v[50:65]
	s_waitcnt lgkmcnt(4)
	v_mfma_f32_32x32x16_bf16 v[34:49], v[142:145], v[162:165], v[34:49]
	v_mfma_f32_32x32x16_bf16 v[18:33], v[152:155], v[156:159], v[18:33]
	v_mfma_f32_32x32x16_bf16 v[2:17], v[152:155], v[162:165], v[2:17]
	ds_read_b128 v[142:145], v134 offset:18496
	ds_read_b128 v[152:155], v134 offset:23104
	ds_read_b128 v[156:159], v148 offset:55360
	ds_read_b128 v[162:165], v148 offset:59968
	s_waitcnt lgkmcnt(5)
	v_mfma_f32_32x32x16_bf16 v[50:65], v[166:169], v[174:177], v[50:65]
	s_waitcnt lgkmcnt(4)
	v_mfma_f32_32x32x16_bf16 v[34:49], v[166:169], v[178:181], v[34:49]
	v_mfma_f32_32x32x16_bf16 v[18:33], v[170:173], v[174:177], v[18:33]
	v_mfma_f32_32x32x16_bf16 v[2:17], v[170:173], v[178:181], v[2:17]
	ds_read_b128 v[166:169], v134 offset:18528
	ds_read_b128 v[170:173], v134 offset:23136
	ds_read_b128 v[174:177], v148 offset:55392
	ds_read_b128 v[178:181], v148 offset:60000
	s_waitcnt lgkmcnt(5)
	v_mfma_f32_32x32x16_bf16 v[50:65], v[142:145], v[156:159], v[50:65]
	s_waitcnt lgkmcnt(4)
	v_mfma_f32_32x32x16_bf16 v[34:49], v[142:145], v[162:165], v[34:49]
	v_mfma_f32_32x32x16_bf16 v[18:33], v[152:155], v[156:159], v[18:33]
	v_mfma_f32_32x32x16_bf16 v[2:17], v[152:155], v[162:165], v[2:17]
	s_waitcnt lgkmcnt(1)
	v_mfma_f32_32x32x16_bf16 v[50:65], v[166:169], v[174:177], v[50:65]
	s_waitcnt lgkmcnt(0)
	v_mfma_f32_32x32x16_bf16 v[34:49], v[166:169], v[178:181], v[34:49]
	v_mfma_f32_32x32x16_bf16 v[18:33], v[170:173], v[174:177], v[18:33]
	v_mfma_f32_32x32x16_bf16 v[2:17], v[170:173], v[178:181], v[2:17]
	s_andn2_b64 vcc, exec, s[12:13]
	s_cbranch_vccnz .LBB0_632
	s_waitcnt vmcnt(14)
	ds_write_b128 v146, v[66:69]
	ds_write_b128 v146, v[70:73] offset:36864
	s_waitcnt vmcnt(12)
	ds_write_b128 v146, v[74:77] offset:4608
	ds_write_b128 v146, v[78:81] offset:41472
	s_waitcnt vmcnt(10)
	ds_write_b128 v146, v[90:93] offset:9216
	ds_write_b128 v146, v[102:105] offset:46080
	s_waitcnt vmcnt(8)
	ds_write_b128 v146, v[114:117] offset:13824
	ds_write_b128 v146, v[118:121] offset:50688
	s_branch .LBB0_632

.LBB0_758:
	ds_read_b128 v[150:153], v134
	ds_read_b128 v[154:157], v134 offset:4608
	ds_read_b128 v[162:165], v147 offset:36864
	ds_read_b128 v[166:169], v147 offset:41472
	ds_read_b128 v[170:173], v134 offset:32
	ds_read_b128 v[174:177], v134 offset:4640
	ds_read_b128 v[178:181], v147 offset:36896
	ds_read_b128 v[182:185], v147 offset:41504
	s_waitcnt lgkmcnt(5)
	v_mfma_f32_32x32x16_bf16 v[50:65], v[150:153], v[162:165], v[50:65]
	s_waitcnt lgkmcnt(4)
	v_mfma_f32_32x32x16_bf16 v[34:49], v[150:153], v[166:169], v[34:49]
	v_mfma_f32_32x32x16_bf16 v[18:33], v[154:157], v[162:165], v[18:33]
	v_mfma_f32_32x32x16_bf16 v[2:17], v[154:157], v[166:169], v[2:17]
	ds_read_b128 v[150:153], v134 offset:64
	ds_read_b128 v[154:157], v134 offset:4672
	ds_read_b128 v[162:165], v147 offset:36928
	ds_read_b128 v[166:169], v147 offset:41536
	s_waitcnt lgkmcnt(5)
	v_mfma_f32_32x32x16_bf16 v[50:65], v[170:173], v[178:181], v[50:65]
	s_waitcnt lgkmcnt(4)
	v_mfma_f32_32x32x16_bf16 v[34:49], v[170:173], v[182:185], v[34:49]
	v_mfma_f32_32x32x16_bf16 v[18:33], v[174:177], v[178:181], v[18:33]
	v_mfma_f32_32x32x16_bf16 v[2:17], v[174:177], v[182:185], v[2:17]
	ds_read_b128 v[170:173], v134 offset:96
	ds_read_b128 v[174:177], v134 offset:4704
	ds_read_b128 v[178:181], v147 offset:36960
	ds_read_b128 v[182:185], v147 offset:41568
	s_waitcnt lgkmcnt(5)
	v_mfma_f32_32x32x16_bf16 v[50:65], v[150:153], v[162:165], v[50:65]
	s_waitcnt lgkmcnt(4)
	v_mfma_f32_32x32x16_bf16 v[34:49], v[150:153], v[166:169], v[34:49]
	v_mfma_f32_32x32x16_bf16 v[18:33], v[154:157], v[162:165], v[18:33]
	v_mfma_f32_32x32x16_bf16 v[2:17], v[154:157], v[166:169], v[2:17]
	s_waitcnt lgkmcnt(1)
	v_mfma_f32_32x32x16_bf16 v[50:65], v[170:173], v[178:181], v[50:65]
	s_waitcnt lgkmcnt(0)
	v_mfma_f32_32x32x16_bf16 v[34:49], v[170:173], v[182:185], v[34:49]
	v_mfma_f32_32x32x16_bf16 v[18:33], v[174:177], v[178:181], v[18:33]
	v_mfma_f32_32x32x16_bf16 v[2:17], v[174:177], v[182:185], v[2:17]
	s_cmp_gt_u32 s3, 13
	s_cbranch_scc1 .Lg3_last_half
	s_waitcnt vmcnt(11)
	ds_write_b128 v146, v[82:85] offset:18432
	ds_write_b128 v146, v[86:89] offset:55296
	s_waitcnt vmcnt(10)
	ds_write_b128 v146, v[94:97] offset:23040
	ds_write_b128 v146, v[98:101] offset:59904
	s_waitcnt vmcnt(9)
	ds_write_b128 v146, v[106:109] offset:27648
	ds_write_b128 v146, v[110:113] offset:64512
	s_waitcnt vmcnt(8)
	ds_write_b128 v146, v[122:125] offset:32256
	ds_write_b128 v148, v[126:129] offset:13824
	s_branch .Lg3_stored
.Lg3_last_half:
	s_waitcnt vmcnt(3)
	ds_write_b128 v146, v[82:85] offset:18432
	ds_write_b128 v146, v[86:89] offset:55296
	s_waitcnt vmcnt(2)
	ds_write_b128 v146, v[94:97] offset:23040
	ds_write_b128 v146, v[98:101] offset:59904
	s_waitcnt vmcnt(1)
	ds_write_b128 v146, v[106:109] offset:27648
	ds_write_b128 v146, v[110:113] offset:64512
	s_waitcnt vmcnt(0)
	ds_write_b128 v146, v[122:125] offset:32256
	ds_write_b128 v148, v[126:129] offset:13824
.Lg3_stored:
	s_cmp_gt_u32 s3, 12
	s_waitcnt lgkmcnt(0)
	s_barrier
	s_cbranch_scc1 .LBB0_760
	v_add_co_u32_e32 v82, vcc, 0x13800000, v144
	s_nop 1
	v_addc_co_u32_e32 v83, vcc, 0, v145, vcc
	v_add_co_u32_e32 v86, vcc, 0x1800000, v142
	global_load_dwordx4 v[82:85], v[82:83], off offset:384
	s_nop 0
	v_addc_co_u32_e32 v87, vcc, 0, v143, vcc
	v_add_co_u32_e32 v94, vcc, 0x13810000, v144
	global_load_dwordx4 v[86:89], v[86:87], off offset:384
	s_nop 0
	v_addc_co_u32_e32 v95, vcc, 0, v145, vcc
	v_add_co_u32_e32 v98, vcc, 0x1810000, v142
	global_load_dwordx4 v[94:97], v[94:95], off offset:384
	s_nop 0
	v_addc_co_u32_e32 v99, vcc, 0, v143, vcc
	v_add_co_u32_e32 v106, vcc, 0x13820000, v144
	global_load_dwordx4 v[98:101], v[98:99], off offset:384
	s_nop 0
	v_addc_co_u32_e32 v107, vcc, 0, v145, vcc
	v_add_co_u32_e32 v110, vcc, 0x1820000, v142
	global_load_dwordx4 v[106:109], v[106:107], off offset:384
	s_nop 0
	v_addc_co_u32_e32 v111, vcc, 0, v143, vcc
	v_add_co_u32_e32 v122, vcc, 0x13830000, v144
	global_load_dwordx4 v[110:113], v[110:111], off offset:384
	s_nop 0
	v_addc_co_u32_e32 v123, vcc, 0, v145, vcc
	v_add_co_u32_e32 v126, vcc, 0x1830000, v142
	global_load_dwordx4 v[122:125], v[122:123], off offset:384
	s_nop 0
	v_addc_co_u32_e32 v127, vcc, 0, v143, vcc
	global_load_dwordx4 v[126:129], v[126:127], off offset:384
.LBB0_760:
	ds_read_b128 v[142:145], v134 offset:18432
	ds_read_b128 v[150:153], v134 offset:23040
	ds_read_b128 v[154:157], v147 offset:55296
	ds_read_b128 v[162:165], v147 offset:59904
	ds_read_b128 v[166:169], v134 offset:18464
	ds_read_b128 v[170:173], v134 offset:23072
	ds_read_b128 v[174:177], v147 offset:55328
	ds_read_b128 v[178:181], v147 offset:59936
	s_waitcnt lgkmcnt(5)
	v_mfma_f32_32x32x16_bf16 v[50:65], v[142:145], v[154:157], v[50:65]
	s_waitcnt lgkmcnt(4)
	v_mfma_f32_32x32x16_bf16 v[34:49], v[142:145], v[162:165], v[34:49]
	v_mfma_f32_32x32x16_bf16 v[18:33], v[150:153], v[154:157], v[18:33]
	v_mfma_f32_32x32x16_bf16 v[2:17], v[150:153], v[162:165], v[2:17]
	ds_read_b128 v[142:145], v134 offset:18496
	ds_read_b128 v[150:153], v134 offset:23104
	ds_read_b128 v[154:157], v147 offset:55360
	ds_read_b128 v[162:165], v147 offset:59968
	s_waitcnt lgkmcnt(5)
	v_mfma_f32_32x32x16_bf16 v[50:65], v[166:169], v[174:177], v[50:65]
	s_waitcnt lgkmcnt(4)
	v_mfma_f32_32x32x16_bf16 v[34:49], v[166:169], v[178:181], v[34:49]
	v_mfma_f32_32x32x16_bf16 v[18:33], v[170:173], v[174:177], v[18:33]
	v_mfma_f32_32x32x16_bf16 v[2:17], v[170:173], v[178:181], v[2:17]
	ds_read_b128 v[166:169], v134 offset:18528
	ds_read_b128 v[170:173], v134 offset:23136
	ds_read_b128 v[174:177], v147 offset:55392
	ds_read_b128 v[178:181], v147 offset:60000
	s_waitcnt lgkmcnt(5)
	v_mfma_f32_32x32x16_bf16 v[50:65], v[142:145], v[154:157], v[50:65]
	s_waitcnt lgkmcnt(4)
	v_mfma_f32_32x32x16_bf16 v[34:49], v[142:145], v[162:165], v[34:49]
	v_mfma_f32_32x32x16_bf16 v[18:33], v[150:153], v[154:157], v[18:33]
	v_mfma_f32_32x32x16_bf16 v[2:17], v[150:153], v[162:165], v[2:17]
	s_waitcnt lgkmcnt(1)
	v_mfma_f32_32x32x16_bf16 v[50:65], v[166:169], v[174:177], v[50:65]
	s_waitcnt lgkmcnt(0)
	v_mfma_f32_32x32x16_bf16 v[34:49], v[166:169], v[178:181], v[34:49]
	v_mfma_f32_32x32x16_bf16 v[18:33], v[170:173], v[174:177], v[18:33]
	v_mfma_f32_32x32x16_bf16 v[2:17], v[170:173], v[178:181], v[2:17]
	s_andn2_b64 vcc, exec, s[10:11]
	s_cbranch_vccnz .LBB0_755
	s_waitcnt vmcnt(14)
	ds_write_b128 v146, v[66:69]
	ds_write_b128 v146, v[70:73] offset:36864
	s_waitcnt vmcnt(12)
	ds_write_b128 v146, v[74:77] offset:4608
	ds_write_b128 v146, v[78:81] offset:41472
	s_waitcnt vmcnt(10)
	ds_write_b128 v146, v[90:93] offset:9216
	ds_write_b128 v146, v[102:105] offset:46080
	s_waitcnt vmcnt(8)
	ds_write_b128 v146, v[114:117] offset:13824
	ds_write_b128 v146, v[118:121] offset:50688
	s_branch .LBB0_755

.LBB0_859:
	v_and_or_b32 v19, s19, 16, v137
	v_lshrrev_b32_e32 v18, 3, v19
	v_cmp_ne_u32_e32 vcc, 3, v18
	s_lshr_b32 s27, s26, 1
	s_lshl_b32 s20, s27, 6
	v_cndmask_b32_e32 v0, 2, v18, vcc
	v_mad_u64_u32 v[2:3], s[0:1], v0, s97, v[130:131]
	v_cmp_lt_i32_e32 vcc, s64, v2
	v_mov_b32_e32 v3, s50
	v_mov_b32_e32 v151, v1
	v_cndmask_b32_e32 v0, v2, v130, vcc
	v_add_u32_e32 v0, s48, v0
	v_cmp_gt_i32_e32 vcc, s52, v0
	v_mov_b32_e32 v2, s49
	s_movk_i32 s0, 0x2000
	v_cndmask_b32_e32 v2, v2, v3, vcc
	v_add_u32_e32 v2, v0, v2
	v_ashrrev_i32_e32 v3, 31, v2
	v_lshlrev_b64 v[2:3], 11, v[2:3]
	v_lshl_add_u64 v[2:3], v[132:133], 0, v[2:3]
	v_lshl_add_u64 v[2:3], s[20:21], 1, v[2:3]
	v_lshl_or_b32 v0, s27, 14, v197
	v_lshl_add_u64 v[2:3], v[2:3], 0, v[150:151]
	s_waitcnt lgkmcnt(7)
	v_lshl_add_u64 v[10:11], v[134:135], 0, v[0:1]
	global_load_dwordx4 v[6:9], v[2:3], off
	s_nop 0
	global_load_dwordx4 v[2:5], v[2:3], off offset:64
	s_waitcnt lgkmcnt(3)
	s_waitcnt lgkmcnt(0)
	v_cmp_gt_u32_e32 vcc, 24, v19
	s_and_b64 s[28:29], s[2:3], vcc
	s_mov_b64 s[98:99], 0x1000
	v_lshl_add_u64 v[104:105], v[10:11], 0, s[98:99]
	v_lshl_add_u64 v[106:107], v[104:105], 0, s[98:99]
	v_lshl_add_u64 v[108:109], v[106:107], 0, s[98:99]
	global_load_dwordx4 v[40:43], v[10:11], off
	global_load_dwordx4 v[44:47], v[10:11], off offset:64
	global_load_dwordx4 v[48:51], v[10:11], off offset:2048
	global_load_dwordx4 v[52:55], v[10:11], off offset:2112
	global_load_dwordx4 v[56:59], v[104:105], off
	global_load_dwordx4 v[60:63], v[104:105], off offset:64
	global_load_dwordx4 v[64:67], v[104:105], off offset:2048
	global_load_dwordx4 v[68:71], v[104:105], off offset:2112
	global_load_dwordx4 v[72:75], v[106:107], off
	global_load_dwordx4 v[76:79], v[106:107], off offset:64
	global_load_dwordx4 v[80:83], v[106:107], off offset:2048
	global_load_dwordx4 v[84:87], v[106:107], off offset:2112
	global_load_dwordx4 v[88:91], v[108:109], off
	global_load_dwordx4 v[92:95], v[108:109], off offset:64
	global_load_dwordx4 v[96:99], v[108:109], off offset:2048
	global_load_dwordx4 v[100:103], v[108:109], off offset:2112
	s_waitcnt vmcnt(15)
	v_mfma_f32_16x16x32_bf16 v[110:113], v[40:43], v[6:9], 0
	s_waitcnt vmcnt(14)
	v_mfma_f32_16x16x32_bf16 v[110:113], v[44:47], v[2:5], v[110:113]
	s_waitcnt vmcnt(13)
	v_mfma_f32_16x16x32_bf16 v[114:117], v[48:51], v[6:9], 0
	s_waitcnt vmcnt(12)
	v_mfma_f32_16x16x32_bf16 v[114:117], v[52:55], v[2:5], v[114:117]
	s_nop 5
	v_and_or_b32 v38, v110, s65, v213
	v_and_or_b32 v39, v111, s65, v221
	v_and_or_b32 v20, v112, s65, v222
	v_and_or_b32 v19, v113, s65, v223
	v_mov_b32_e32 v22, v38
	v_max_f32_e32 v118, v22, v39
	v_min_f32_e32 v119, v22, v39
	v_max_f32_e32 v22, v118, v20
	v_med3_f32 v23, v118, v119, v20
	v_min_f32_e32 v24, v119, v20
	v_max_f32_e32 v118, v22, v19
	v_med3_f32 v119, v22, v23, v19
	v_med3_f32 v120, v23, v24, v19
	v_min_f32_e32 v121, v24, v19
	s_waitcnt vmcnt(11)
	v_mfma_f32_16x16x32_bf16 v[110:113], v[56:59], v[6:9], 0
	s_waitcnt vmcnt(10)
	v_mfma_f32_16x16x32_bf16 v[110:113], v[60:63], v[2:5], v[110:113]
	v_and_or_b32 v38, v114, s65, v224
	v_and_or_b32 v39, v115, s65, v225
	v_and_or_b32 v20, v116, s65, v226
	v_and_or_b32 v19, v117, s65, v227
	v_max_f32_e32 v22, v118, v38
	v_med3_f32 v23, v118, v119, v38
	v_med3_f32 v24, v119, v120, v38
	v_med3_f32 v25, v120, v121, v38
	v_min_f32_e32 v26, v121, v38
	v_max_f32_e32 v118, v22, v39
	v_med3_f32 v119, v22, v23, v39
	v_med3_f32 v120, v23, v24, v39
	v_med3_f32 v121, v24, v25, v39
	v_med3_f32 v122, v25, v26, v39
	v_min_f32_e32 v123, v26, v39
	v_max_f32_e32 v22, v118, v20
	v_med3_f32 v23, v118, v119, v20
	v_med3_f32 v24, v119, v120, v20
	v_med3_f32 v25, v120, v121, v20
	v_med3_f32 v26, v121, v122, v20
	v_med3_f32 v27, v122, v123, v20
	v_min_f32_e32 v28, v123, v20
	v_max_f32_e32 v118, v22, v19
	v_med3_f32 v119, v22, v23, v19
	v_med3_f32 v120, v23, v24, v19
	v_med3_f32 v121, v24, v25, v19
	v_med3_f32 v122, v25, v26, v19
	v_med3_f32 v123, v26, v27, v19
	v_med3_f32 v124, v27, v28, v19
	v_min_f32_e32 v125, v28, v19
	s_waitcnt vmcnt(9)
	v_mfma_f32_16x16x32_bf16 v[114:117], v[64:67], v[6:9], 0
	s_waitcnt vmcnt(8)
	v_mfma_f32_16x16x32_bf16 v[114:117], v[68:71], v[2:5], v[114:117]
	v_and_or_b32 v38, v110, s65, v228
	v_and_or_b32 v39, v111, s65, v229
	v_and_or_b32 v20, v112, s65, v230
	v_and_or_b32 v19, v113, s65, v231
	v_max_f32_e32 v22, v118, v38
	v_med3_f32 v23, v118, v119, v38
	v_med3_f32 v24, v119, v120, v38
	v_med3_f32 v25, v120, v121, v38
	v_med3_f32 v26, v121, v122, v38
	v_med3_f32 v27, v122, v123, v38
	v_med3_f32 v28, v123, v124, v38
	v_med3_f32 v29, v124, v125, v38
	v_min_f32_e32 v30, v125, v38
	v_max_f32_e32 v118, v22, v39
	v_med3_f32 v119, v22, v23, v39
	v_med3_f32 v120, v23, v24, v39
	v_med3_f32 v121, v24, v25, v39
	v_med3_f32 v122, v25, v26, v39
	v_med3_f32 v123, v26, v27, v39
	v_med3_f32 v124, v27, v28, v39
	v_med3_f32 v125, v28, v29, v39
	v_med3_f32 v126, v29, v30, v39
	v_min_f32_e32 v127, v30, v39
	v_max_f32_e32 v22, v118, v20
	v_med3_f32 v23, v118, v119, v20
	v_med3_f32 v24, v119, v120, v20
	v_med3_f32 v25, v120, v121, v20
	v_med3_f32 v26, v121, v122, v20
	v_med3_f32 v27, v122, v123, v20
	v_med3_f32 v28, v123, v124, v20
	v_med3_f32 v29, v124, v125, v20
	v_med3_f32 v30, v125, v126, v20
	v_med3_f32 v31, v126, v127, v20
	v_min_f32_e32 v32, v127, v20
	v_max_f32_e32 v118, v22, v19
	v_med3_f32 v119, v22, v23, v19
	v_med3_f32 v120, v23, v24, v19
	v_med3_f32 v121, v24, v25, v19
	v_med3_f32 v122, v25, v26, v19
	v_med3_f32 v123, v26, v27, v19
	v_med3_f32 v124, v27, v28, v19
	v_med3_f32 v125, v28, v29, v19
	v_med3_f32 v126, v29, v30, v19
	v_med3_f32 v127, v30, v31, v19
	v_med3_f32 v128, v31, v32, v19
	v_min_f32_e32 v129, v32, v19
	s_waitcnt vmcnt(7)
	v_mfma_f32_16x16x32_bf16 v[110:113], v[72:75], v[6:9], 0
	s_waitcnt vmcnt(6)
	v_mfma_f32_16x16x32_bf16 v[110:113], v[76:79], v[2:5], v[110:113]
	v_and_or_b32 v38, v114, s65, v232
	v_and_or_b32 v39, v115, s65, v233
	v_and_or_b32 v20, v116, s65, v234
	v_and_or_b32 v19, v117, s65, v235
	v_max_f32_e32 v22, v118, v38
	v_med3_f32 v23, v118, v119, v38
	v_med3_f32 v24, v119, v120, v38
	v_med3_f32 v25, v120, v121, v38
	v_med3_f32 v26, v121, v122, v38
	v_med3_f32 v27, v122, v123, v38
	v_med3_f32 v28, v123, v124, v38
	v_med3_f32 v29, v124, v125, v38
	v_med3_f32 v30, v125, v126, v38
	v_med3_f32 v31, v126, v127, v38
	v_med3_f32 v32, v127, v128, v38
	v_med3_f32 v33, v128, v129, v38
	v_min_f32_e32 v34, v129, v38
	v_max_f32_e32 v118, v22, v39
	v_med3_f32 v119, v22, v23, v39
	v_med3_f32 v120, v23, v24, v39
	v_med3_f32 v121, v24, v25, v39
	v_med3_f32 v122, v25, v26, v39
	v_med3_f32 v123, v26, v27, v39
	v_med3_f32 v124, v27, v28, v39
	v_med3_f32 v125, v28, v29, v39
	v_med3_f32 v126, v29, v30, v39
	v_med3_f32 v127, v30, v31, v39
	v_med3_f32 v128, v31, v32, v39
	v_med3_f32 v129, v32, v33, v39
	v_med3_f32 v10, v33, v34, v39
	v_min_f32_e32 v11, v34, v39
	v_max_f32_e32 v22, v118, v20
	v_med3_f32 v23, v118, v119, v20
	v_med3_f32 v24, v119, v120, v20
	v_med3_f32 v25, v120, v121, v20
	v_med3_f32 v26, v121, v122, v20
	v_med3_f32 v27, v122, v123, v20
	v_med3_f32 v28, v123, v124, v20
	v_med3_f32 v29, v124, v125, v20
	v_med3_f32 v30, v125, v126, v20
	v_med3_f32 v31, v126, v127, v20
	v_med3_f32 v32, v127, v128, v20
	v_med3_f32 v33, v128, v129, v20
	v_med3_f32 v34, v129, v10, v20
	v_med3_f32 v35, v10, v11, v20
	v_min_f32_e32 v36, v11, v20
	v_max_f32_e32 v118, v22, v19
	v_med3_f32 v119, v22, v23, v19
	v_med3_f32 v120, v23, v24, v19
	v_med3_f32 v121, v24, v25, v19
	v_med3_f32 v122, v25, v26, v19
	v_med3_f32 v123, v26, v27, v19
	v_med3_f32 v124, v27, v28, v19
	v_med3_f32 v125, v28, v29, v19
	v_med3_f32 v126, v29, v30, v19
	v_med3_f32 v127, v30, v31, v19
	v_med3_f32 v128, v31, v32, v19
	v_med3_f32 v129, v32, v33, v19
	v_med3_f32 v10, v33, v34, v19
	v_med3_f32 v11, v34, v35, v19
	v_med3_f32 v16, v35, v36, v19
	v_min_f32_e32 v17, v36, v19
	s_waitcnt vmcnt(5)
	v_mfma_f32_16x16x32_bf16 v[114:117], v[80:83], v[6:9], 0
	s_waitcnt vmcnt(4)
	v_mfma_f32_16x16x32_bf16 v[114:117], v[84:87], v[2:5], v[114:117]
	v_and_or_b32 v38, v110, s65, v236
	v_and_or_b32 v39, v111, s65, v237
	v_and_or_b32 v20, v112, s65, v238
	v_and_or_b32 v19, v113, s65, v239
	v_max_f32_e32 v22, v118, v38
	v_med3_f32 v23, v118, v119, v38
	v_med3_f32 v24, v119, v120, v38
	v_med3_f32 v25, v120, v121, v38
	v_med3_f32 v26, v121, v122, v38
	v_med3_f32 v27, v122, v123, v38
	v_med3_f32 v28, v123, v124, v38
	v_med3_f32 v29, v124, v125, v38
	v_med3_f32 v30, v125, v126, v38
	v_med3_f32 v31, v126, v127, v38
	v_med3_f32 v32, v127, v128, v38
	v_med3_f32 v33, v128, v129, v38
	v_med3_f32 v34, v129, v10, v38
	v_med3_f32 v35, v10, v11, v38
	v_med3_f32 v36, v11, v16, v38
	v_med3_f32 v37, v16, v17, v38
	v_max_f32_e32 v118, v22, v39
	v_med3_f32 v119, v22, v23, v39
	v_med3_f32 v120, v23, v24, v39
	v_med3_f32 v121, v24, v25, v39
	v_med3_f32 v122, v25, v26, v39
	v_med3_f32 v123, v26, v27, v39
	v_med3_f32 v124, v27, v28, v39
	v_med3_f32 v125, v28, v29, v39
	v_med3_f32 v126, v29, v30, v39
	v_med3_f32 v127, v30, v31, v39
	v_med3_f32 v128, v31, v32, v39
	v_med3_f32 v129, v32, v33, v39
	v_med3_f32 v10, v33, v34, v39
	v_med3_f32 v11, v34, v35, v39
	v_med3_f32 v16, v35, v36, v39
	v_med3_f32 v17, v36, v37, v39
	v_max_f32_e32 v22, v118, v20
	v_med3_f32 v23, v118, v119, v20
	v_med3_f32 v24, v119, v120, v20
	v_med3_f32 v25, v120, v121, v20
	v_med3_f32 v26, v121, v122, v20
	v_med3_f32 v27, v122, v123, v20
	v_med3_f32 v28, v123, v124, v20
	v_med3_f32 v29, v124, v125, v20
	v_med3_f32 v30, v125, v126, v20
	v_med3_f32 v31, v126, v127, v20
	v_med3_f32 v32, v127, v128, v20
	v_med3_f32 v33, v128, v129, v20
	v_med3_f32 v34, v129, v10, v20
	v_med3_f32 v35, v10, v11, v20
	v_med3_f32 v36, v11, v16, v20
	v_med3_f32 v37, v16, v17, v20
	v_max_f32_e32 v118, v22, v19
	v_med3_f32 v119, v22, v23, v19
	v_med3_f32 v120, v23, v24, v19
	v_med3_f32 v121, v24, v25, v19
	v_med3_f32 v122, v25, v26, v19
	v_med3_f32 v123, v26, v27, v19
	v_med3_f32 v124, v27, v28, v19
	v_med3_f32 v125, v28, v29, v19
	v_med3_f32 v126, v29, v30, v19
	v_med3_f32 v127, v30, v31, v19
	v_med3_f32 v128, v31, v32, v19
	v_med3_f32 v129, v32, v33, v19
	v_med3_f32 v10, v33, v34, v19
	v_med3_f32 v11, v34, v35, v19
	v_med3_f32 v16, v35, v36, v19
	v_med3_f32 v17, v36, v37, v19
	s_waitcnt vmcnt(3)
	v_mfma_f32_16x16x32_bf16 v[110:113], v[88:91], v[6:9], 0
	s_waitcnt vmcnt(2)
	v_mfma_f32_16x16x32_bf16 v[110:113], v[92:95], v[2:5], v[110:113]
	v_and_or_b32 v38, v114, s65, v240
	v_and_or_b32 v39, v115, s65, v241
	v_and_or_b32 v20, v116, s65, v242
	v_and_or_b32 v19, v117, s65, v243
	v_max_f32_e32 v22, v118, v38
	v_med3_f32 v23, v118, v119, v38
	v_med3_f32 v24, v119, v120, v38
	v_med3_f32 v25, v120, v121, v38
	v_med3_f32 v26, v121, v122, v38
	v_med3_f32 v27, v122, v123, v38
	v_med3_f32 v28, v123, v124, v38
	v_med3_f32 v29, v124, v125, v38
	v_med3_f32 v30, v125, v126, v38
	v_med3_f32 v31, v126, v127, v38
	v_med3_f32 v32, v127, v128, v38
	v_med3_f32 v33, v128, v129, v38
	v_med3_f32 v34, v129, v10, v38
	v_med3_f32 v35, v10, v11, v38
	v_med3_f32 v36, v11, v16, v38
	v_med3_f32 v37, v16, v17, v38
	v_max_f32_e32 v118, v22, v39
	v_med3_f32 v119, v22, v23, v39
	v_med3_f32 v120, v23, v24, v39
	v_med3_f32 v121, v24, v25, v39
	v_med3_f32 v122, v25, v26, v39
	v_med3_f32 v123, v26, v27, v39
	v_med3_f32 v124, v27, v28, v39
	v_med3_f32 v125, v28, v29, v39
	v_med3_f32 v126, v29, v30, v39
	v_med3_f32 v127, v30, v31, v39
	v_med3_f32 v128, v31, v32, v39
	v_med3_f32 v129, v32, v33, v39
	v_med3_f32 v10, v33, v34, v39
	v_med3_f32 v11, v34, v35, v39
	v_med3_f32 v16, v35, v36, v39
	v_med3_f32 v17, v36, v37, v39
	v_max_f32_e32 v22, v118, v20
	v_med3_f32 v23, v118, v119, v20
	v_med3_f32 v24, v119, v120, v20
	v_med3_f32 v25, v120, v121, v20
	v_med3_f32 v26, v121, v122, v20
	v_med3_f32 v27, v122, v123, v20
	v_med3_f32 v28, v123, v124, v20
	v_med3_f32 v29, v124, v125, v20
	v_med3_f32 v30, v125, v126, v20
	v_med3_f32 v31, v126, v127, v20
	v_med3_f32 v32, v127, v128, v20
	v_med3_f32 v33, v128, v129, v20
	v_med3_f32 v34, v129, v10, v20
	v_med3_f32 v35, v10, v11, v20
	v_med3_f32 v36, v11, v16, v20
	v_med3_f32 v37, v16, v17, v20
	v_max_f32_e32 v118, v22, v19
	v_med3_f32 v119, v22, v23, v19
	v_med3_f32 v120, v23, v24, v19
	v_med3_f32 v121, v24, v25, v19
	v_med3_f32 v122, v25, v26, v19
	v_med3_f32 v123, v26, v27, v19
	v_med3_f32 v124, v27, v28, v19
	v_med3_f32 v125, v28, v29, v19
	v_med3_f32 v126, v29, v30, v19
	v_med3_f32 v127, v30, v31, v19
	v_med3_f32 v128, v31, v32, v19
	v_med3_f32 v129, v32, v33, v19
	v_med3_f32 v10, v33, v34, v19
	v_med3_f32 v11, v34, v35, v19
	v_med3_f32 v16, v35, v36, v19
	v_med3_f32 v17, v36, v37, v19
	s_waitcnt vmcnt(1)
	v_mfma_f32_16x16x32_bf16 v[114:117], v[96:99], v[6:9], 0
	s_waitcnt vmcnt(0)
	v_mfma_f32_16x16x32_bf16 v[114:117], v[100:103], v[2:5], v[114:117]
	v_and_or_b32 v38, v110, s65, v244
	v_and_or_b32 v39, v111, s65, v245
	v_and_or_b32 v20, v112, s65, v246
	v_and_or_b32 v19, v113, s65, v247
	v_max_f32_e32 v22, v118, v38
	v_med3_f32 v23, v118, v119, v38
	v_med3_f32 v24, v119, v120, v38
	v_med3_f32 v25, v120, v121, v38
	v_med3_f32 v26, v121, v122, v38
	v_med3_f32 v27, v122, v123, v38
	v_med3_f32 v28, v123, v124, v38
	v_med3_f32 v29, v124, v125, v38
	v_med3_f32 v30, v125, v126, v38
	v_med3_f32 v31, v126, v127, v38
	v_med3_f32 v32, v127, v128, v38
	v_med3_f32 v33, v128, v129, v38
	v_med3_f32 v34, v129, v10, v38
	v_med3_f32 v35, v10, v11, v38
	v_med3_f32 v36, v11, v16, v38
	v_med3_f32 v37, v16, v17, v38
	v_max_f32_e32 v118, v22, v39
	v_med3_f32 v119, v22, v23, v39
	v_med3_f32 v120, v23, v24, v39
	v_med3_f32 v121, v24, v25, v39
	v_med3_f32 v122, v25, v26, v39
	v_med3_f32 v123, v26, v27, v39
	v_med3_f32 v124, v27, v28, v39
	v_med3_f32 v125, v28, v29, v39
	v_med3_f32 v126, v29, v30, v39
	v_med3_f32 v127, v30, v31, v39
	v_med3_f32 v128, v31, v32, v39
	v_med3_f32 v129, v32, v33, v39
	v_med3_f32 v10, v33, v34, v39
	v_med3_f32 v11, v34, v35, v39
	v_med3_f32 v16, v35, v36, v39
	v_med3_f32 v17, v36, v37, v39
	v_max_f32_e32 v22, v118, v20
	v_med3_f32 v23, v118, v119, v20
	v_med3_f32 v24, v119, v120, v20
	v_med3_f32 v25, v120, v121, v20
	v_med3_f32 v26, v121, v122, v20
	v_med3_f32 v27, v122, v123, v20
	v_med3_f32 v28, v123, v124, v20
	v_med3_f32 v29, v124, v125, v20
	v_med3_f32 v30, v125, v126, v20
	v_med3_f32 v31, v126, v127, v20
	v_med3_f32 v32, v127, v128, v20
	v_med3_f32 v33, v128, v129, v20
	v_med3_f32 v34, v129, v10, v20
	v_med3_f32 v35, v10, v11, v20
	v_med3_f32 v36, v11, v16, v20
	v_med3_f32 v37, v16, v17, v20
	v_max_f32_e32 v118, v22, v19
	v_med3_f32 v119, v22, v23, v19
	v_med3_f32 v120, v23, v24, v19
	v_med3_f32 v121, v24, v25, v19
	v_med3_f32 v122, v25, v26, v19
	v_med3_f32 v123, v26, v27, v19
	v_med3_f32 v124, v27, v28, v19
	v_med3_f32 v125, v28, v29, v19
	v_med3_f32 v126, v29, v30, v19
	v_med3_f32 v127, v30, v31, v19
	v_med3_f32 v128, v31, v32, v19
	v_med3_f32 v129, v32, v33, v19
	v_med3_f32 v10, v33, v34, v19
	v_med3_f32 v11, v34, v35, v19
	v_med3_f32 v16, v35, v36, v19
	v_med3_f32 v17, v36, v37, v19
	v_and_or_b32 v38, v114, s65, v248
	v_and_or_b32 v39, v115, s65, v249
	v_and_or_b32 v20, v116, s65, v250
	v_and_or_b32 v19, v117, s65, v251
	v_max_f32_e32 v22, v118, v38
	v_med3_f32 v23, v118, v119, v38
	v_med3_f32 v24, v119, v120, v38
	v_med3_f32 v25, v120, v121, v38
	v_med3_f32 v26, v121, v122, v38
	v_med3_f32 v27, v122, v123, v38
	v_med3_f32 v28, v123, v124, v38
	v_med3_f32 v29, v124, v125, v38
	v_med3_f32 v30, v125, v126, v38
	v_med3_f32 v31, v126, v127, v38
	v_med3_f32 v32, v127, v128, v38
	v_med3_f32 v33, v128, v129, v38
	v_med3_f32 v34, v129, v10, v38
	v_med3_f32 v35, v10, v11, v38
	v_med3_f32 v36, v11, v16, v38
	v_med3_f32 v37, v16, v17, v38
	v_max_f32_e32 v118, v22, v39
	v_med3_f32 v119, v22, v23, v39
	v_med3_f32 v120, v23, v24, v39
	v_med3_f32 v121, v24, v25, v39
	v_med3_f32 v122, v25, v26, v39
	v_med3_f32 v123, v26, v27, v39
	v_med3_f32 v124, v27, v28, v39
	v_med3_f32 v125, v28, v29, v39
	v_med3_f32 v126, v29, v30, v39
	v_med3_f32 v127, v30, v31, v39
	v_med3_f32 v128, v31, v32, v39
	v_med3_f32 v129, v32, v33, v39
	v_med3_f32 v10, v33, v34, v39
	v_med3_f32 v11, v34, v35, v39
	v_med3_f32 v16, v35, v36, v39
	v_med3_f32 v17, v36, v37, v39
	v_max_f32_e32 v22, v118, v20
	v_med3_f32 v23, v118, v119, v20
	v_med3_f32 v24, v119, v120, v20
	v_med3_f32 v25, v120, v121, v20
	v_med3_f32 v26, v121, v122, v20
	v_med3_f32 v27, v122, v123, v20
	v_med3_f32 v28, v123, v124, v20
	v_med3_f32 v29, v124, v125, v20
	v_med3_f32 v30, v125, v126, v20
	v_med3_f32 v31, v126, v127, v20
	v_med3_f32 v32, v127, v128, v20
	v_med3_f32 v33, v128, v129, v20
	v_med3_f32 v34, v129, v10, v20
	v_med3_f32 v35, v10, v11, v20
	v_med3_f32 v36, v11, v16, v20
	v_med3_f32 v37, v16, v17, v20
	v_max_f32_e32 v21, v22, v19
	v_med3_f32 v5, v22, v23, v19
	v_med3_f32 v4, v23, v24, v19
	v_med3_f32 v6, v24, v25, v19
	v_med3_f32 v7, v25, v26, v19
	v_med3_f32 v8, v26, v27, v19
	v_med3_f32 v9, v27, v28, v19
	v_med3_f32 v10, v28, v29, v19
	v_med3_f32 v11, v29, v30, v19
	v_med3_f32 v12, v30, v31, v19
	v_med3_f32 v13, v31, v32, v19
	v_med3_f32 v14, v32, v33, v19
	v_med3_f32 v15, v33, v34, v19
	v_med3_f32 v16, v34, v35, v19
	v_med3_f32 v17, v35, v36, v19
	v_med3_f32 v0, v36, v37, v19
	ds_bpermute_b32 v2, v214, v21
	ds_bpermute_b32 v34, v214, v0
	ds_bpermute_b32 v33, v214, v17
	ds_bpermute_b32 v32, v214, v16
	ds_bpermute_b32 v31, v214, v15
	ds_bpermute_b32 v30, v214, v14
	s_waitcnt lgkmcnt(5)
	v_max_f32_e32 v2, v2, v2
	ds_bpermute_b32 v29, v214, v13
	v_max_f32_e32 v0, v0, v2
	s_waitcnt lgkmcnt(5)
	v_max_f32_e32 v2, v34, v34
	ds_bpermute_b32 v28, v214, v12
	v_max_f32_e32 v2, v21, v2
	s_waitcnt lgkmcnt(5)
	v_max_f32_e32 v21, v33, v33
	ds_bpermute_b32 v3, v214, v5
	ds_bpermute_b32 v27, v214, v11
	v_max_f32_e32 v5, v5, v21
	s_waitcnt lgkmcnt(6)
	v_max_f32_e32 v21, v32, v32
	ds_bpermute_b32 v20, v214, v4
	ds_bpermute_b32 v26, v214, v10
	v_max_f32_e32 v4, v4, v21
	s_waitcnt lgkmcnt(7)
	v_max_f32_e32 v21, v31, v31
	ds_bpermute_b32 v22, v214, v6
	ds_bpermute_b32 v25, v214, v9
	v_max_f32_e32 v6, v6, v21
	s_waitcnt lgkmcnt(8)
	v_max_f32_e32 v21, v30, v30
	ds_bpermute_b32 v23, v214, v7
	ds_bpermute_b32 v24, v214, v8
	v_max_f32_e32 v7, v7, v21
	s_waitcnt lgkmcnt(9)
	v_max_f32_e32 v21, v29, v29
	v_max_f32_e32 v8, v8, v21
	s_waitcnt lgkmcnt(8)
	v_max_f32_e32 v21, v28, v28
	v_max_f32_e32 v9, v9, v21
	s_waitcnt lgkmcnt(6)
	v_max_f32_e32 v21, v27, v27
	v_max_f32_e32 v10, v10, v21
	s_waitcnt lgkmcnt(4)
	v_max_f32_e32 v21, v26, v26
	v_max_f32_e32 v11, v11, v21
	s_waitcnt lgkmcnt(2)
	v_max_f32_e32 v21, v25, v25
	v_max_f32_e32 v12, v12, v21
	s_waitcnt lgkmcnt(0)
	v_max_f32_e32 v21, v24, v24
	v_max_f32_e32 v13, v13, v21
	v_max_f32_e32 v21, v23, v23
	v_max_f32_e32 v14, v14, v21
	v_max_f32_e32 v21, v22, v22
	v_max_f32_e32 v20, v20, v20
	v_max_f32_e32 v3, v3, v3
	v_max_f32_e32 v15, v15, v21
	v_max_f32_e32 v16, v16, v20
	v_max_f32_e32 v3, v17, v3
	v_max_f32_e32 v17, v2, v11
	v_min_f32_e32 v2, v2, v11
	v_max_f32_e32 v11, v5, v12
	v_min_f32_e32 v5, v5, v12
	v_max_f32_e32 v12, v4, v13
	v_min_f32_e32 v4, v4, v13
	v_max_f32_e32 v13, v6, v14
	v_min_f32_e32 v6, v6, v14
	v_max_f32_e32 v14, v7, v15
	v_min_f32_e32 v7, v7, v15
	v_max_f32_e32 v15, v8, v16
	v_min_f32_e32 v8, v8, v16
	v_max_f32_e32 v16, v9, v3
	v_min_f32_e32 v3, v9, v3
	v_max_f32_e32 v9, v10, v0
	v_min_f32_e32 v0, v10, v0
	v_max_f32_e32 v10, v17, v14
	v_min_f32_e32 v14, v17, v14
	v_max_f32_e32 v17, v11, v15
	v_min_f32_e32 v11, v11, v15
	v_max_f32_e32 v15, v12, v16
	v_min_f32_e32 v12, v12, v16
	v_max_f32_e32 v16, v13, v9
	v_min_f32_e32 v9, v13, v9
	v_max_f32_e32 v13, v2, v7
	v_min_f32_e32 v2, v2, v7
	v_max_f32_e32 v7, v5, v8
	v_min_f32_e32 v5, v5, v8
	v_max_f32_e32 v8, v4, v3
	v_min_f32_e32 v3, v4, v3
	v_max_f32_e32 v4, v6, v0
	v_min_f32_e32 v0, v6, v0
	v_max_f32_e32 v6, v10, v15
	v_min_f32_e32 v10, v10, v15
	v_max_f32_e32 v15, v17, v16
	v_min_f32_e32 v16, v17, v16
	v_max_f32_e32 v17, v14, v12
	v_min_f32_e32 v12, v14, v12
	v_max_f32_e32 v14, v11, v9
	v_min_f32_e32 v9, v11, v9
	v_max_f32_e32 v11, v13, v8
	v_min_f32_e32 v8, v13, v8
	v_max_f32_e32 v13, v7, v4
	v_min_f32_e32 v4, v7, v4
	v_max_f32_e32 v20, v2, v3
	v_min_f32_e32 v3, v2, v3
	v_max_f32_e32 v22, v5, v0
	v_min_f32_e32 v25, v5, v0
	v_max_f32_e32 v24, v6, v15
	v_min_f32_e32 v7, v6, v15
	v_max_f32_e32 v15, v10, v16
	v_min_f32_e32 v2, v10, v16
	v_max_f32_e32 v23, v17, v14
	v_min_f32_e32 v6, v17, v14
	v_max_f32_e32 v14, v12, v9
	v_min_f32_e32 v0, v12, v9
	v_max_f32_e32 v29, v11, v13
	v_min_f32_e32 v11, v11, v13
	v_max_f32_e32 v21, v8, v4
	v_min_f32_e32 v5, v8, v4
	v_max_f32_e32 v26, v20, v22
	v_min_f32_e32 v8, v20, v22
	v_max_f32_e32 v16, v3, v25
	v_min_f32_e32 v3, v3, v25
	ds_bpermute_b32 v4, v215, v24
	ds_bpermute_b32 v22, v215, v7
	ds_bpermute_b32 v12, v215, v15
	ds_bpermute_b32 v30, v215, v2
	ds_bpermute_b32 v9, v215, v23
	ds_bpermute_b32 v27, v215, v6
	ds_bpermute_b32 v17, v215, v14
	ds_bpermute_b32 v32, v215, v0
	ds_bpermute_b32 v10, v215, v29
	ds_bpermute_b32 v28, v215, v11
	ds_bpermute_b32 v20, v215, v21
	ds_bpermute_b32 v33, v215, v5
	ds_bpermute_b32 v13, v215, v26
	ds_bpermute_b32 v31, v215, v8
	ds_bpermute_b32 v25, v215, v16
	ds_bpermute_b32 v34, v215, v3
	s_and_saveexec_b64 s[0:1], s[28:29]
	s_cbranch_execz .LBB0_858
	s_waitcnt lgkmcnt(3)
	v_max_f32_e32 v13, v13, v13
	v_max_f32_e32 v2, v2, v2
	s_waitcnt lgkmcnt(1)
	v_max_f32_e32 v25, v25, v25
	v_max_f32_e32 v7, v7, v7
	v_max_f32_e32 v13, v2, v13
	v_max_f32_e32 v2, v9, v9
	v_max_f32_e32 v5, v5, v5
	s_waitcnt lgkmcnt(0)
	v_max_f32_e32 v19, v34, v34
	v_max_f32_e32 v24, v24, v24
	v_max_f32_e32 v25, v7, v25
	v_max_f32_e32 v7, v17, v17
	v_max_f32_e32 v17, v20, v20
	v_max_f32_e32 v6, v6, v6
	v_max_f32_e32 v20, v5, v2
	v_max_f32_e32 v2, v10, v10
	v_max_f32_e32 v0, v0, v0
	v_max_f32_e32 v19, v24, v19
	v_max_f32_e32 v24, v32, v32
	v_max_f32_e32 v29, v29, v29
	v_max_f32_e32 v32, v33, v33
	v_max_f32_e32 v23, v23, v23
	v_max_f32_e32 v30, v30, v30
	v_max_f32_e32 v26, v26, v26
	v_max_f32_e32 v31, v31, v31
	v_max_f32_e32 v15, v15, v15
	v_max_f32_e32 v27, v27, v27
	v_max_f32_e32 v21, v21, v21
	v_max_f32_e32 v28, v28, v28
	v_max_f32_e32 v14, v14, v14
	v_max_f32_e32 v22, v22, v22
	v_max_f32_e32 v16, v16, v16
	v_max_f32_e32 v11, v11, v11
	v_max_f32_e32 v17, v6, v17
	v_max_f32_e32 v6, v12, v12
	v_max_f32_e32 v8, v8, v8
	v_max_f32_e32 v0, v0, v2
	v_max_f32_e32 v2, v4, v4
	v_max_f32_e32 v3, v3, v3
	v_max_f32_e32 v24, v29, v24
	v_max_f32_e32 v23, v23, v32
	v_max_f32_e32 v26, v26, v30
	v_max_f32_e32 v15, v15, v31
	v_max_f32_e32 v21, v21, v27
	v_max_f32_e32 v14, v14, v28
	v_max_f32_e32 v16, v16, v22
	v_max_f32_e32 v11, v11, v7
	v_max_f32_e32 v12, v8, v6
	v_max_f32_e32 v10, v3, v2
	v_min_f32_e32 v29, v19, v24
	v_min_f32_e32 v30, v23, v26
	v_min_f32_e32 v27, v15, v21
	v_min_f32_e32 v22, v14, v16
	v_min_f32_e32 v7, v25, v11
	v_min_f32_e32 v6, v17, v12
	v_min_f32_e32 v9, v13, v20
	v_min_f32_e32 v33, v0, v10
	v_min_f32_e32 v32, v29, v30
	v_min_f32_e32 v28, v27, v22
	v_min_f32_e32 v8, v7, v6
	v_min_f32_e32 v2, v9, v33
	v_min_f32_e32 v31, v32, v28
	v_min_f32_e32 v3, v8, v2
	v_max_f32_e32 v28, v32, v28
	v_max_f32_e32 v2, v8, v2
	v_min_f32_e32 v5, v31, v3
	v_max_f32_e32 v4, v31, v3
	v_min_f32_e32 v3, v28, v2
	v_max_f32_e32 v2, v28, v2
	v_max_f32_e32 v28, v29, v30
	v_max_f32_e32 v22, v27, v22
	v_max_f32_e32 v6, v7, v6
	v_max_f32_e32 v7, v9, v33
	v_min_f32_e32 v8, v28, v22
	v_min_f32_e32 v27, v6, v7
	v_max_f32_e32 v22, v28, v22
	v_max_f32_e32 v6, v6, v7
	v_min_f32_e32 v7, v22, v6
	v_max_f32_e32 v6, v22, v6
	v_max_f32_e32 v19, v19, v24
	v_max_f32_e32 v22, v23, v26
	v_max_f32_e32 v15, v15, v21
	v_max_f32_e32 v14, v14, v16
	v_max_f32_e32 v24, v25, v11
	v_max_f32_e32 v17, v17, v12
	v_max_f32_e32 v20, v13, v20
	v_max_f32_e32 v0, v0, v10
	v_min_f32_e32 v23, v19, v22
	v_min_f32_e32 v16, v15, v14
	v_min_f32_e32 v11, v24, v17
	v_min_f32_e32 v10, v20, v0
	v_min_f32_e32 v21, v23, v16
	v_min_f32_e32 v12, v11, v10
	v_min_f32_e32 v13, v21, v12
	v_max_f32_e32 v12, v21, v12
	v_max_f32_e32 v16, v23, v16
	v_max_f32_e32 v10, v11, v10
	v_max_f32_e32 v19, v19, v22
	v_max_f32_e32 v14, v15, v14
	v_max_f32_e32 v21, v24, v17
	v_max_f32_e32 v0, v20, v0
	v_min_f32_e32 v11, v16, v10
	v_max_f32_e32 v10, v16, v10
	v_min_f32_e32 v15, v19, v14
	v_min_f32_e32 v16, v21, v0
	v_max_f32_e32 v14, v19, v14
	v_max_f32_e32 v0, v21, v0
	v_min_f32_e32 v17, v15, v16
	v_max_f32_e32 v16, v15, v16
	v_min_f32_e32 v15, v14, v0
	v_max_f32_e32 v14, v14, v0
	v_lshlrev_b32_e32 v0, 10, v18
	v_add3_u32 v0, v252, v0, s20
	v_min_f32_e32 v9, v8, v27
	v_max_f32_e32 v8, v8, v27
	ds_write_b128 v0, v[14:17]
	ds_write_b128 v0, v[10:13] offset:16
	ds_write_b128 v0, v[6:9] offset:32
	ds_write_b128 v0, v[2:5] offset:48
	s_branch .LBB0_858

.LBB0_867:
	s_waitcnt lgkmcnt(14)
	ds_read_b32 v4, v3
	ds_read_b32 v5, v2
	s_waitcnt lgkmcnt(1)
	v_and_b32_e32 v6, 0xffffff80, v4
	s_waitcnt lgkmcnt(0)
	v_and_b32_e32 v7, 0xffffff80, v5
	v_add_f32_e32 v6, v6, v7
	v_cndmask_b32_e64 v6, v212, v6, s[4:5]
	v_ashrrev_i32_e32 v7, 31, v6
	v_or_b32_e32 v7, 0x80000000, v7
	v_xor_b32_e32 v7, v7, v6
	s_mov_b32 s0, 0
	s_or_b32 s1, s0, 0x80000000
	v_cmp_le_u32_e64 s[42:43], s1, v7
	s_bcnt1_i32_b64 s41, s[42:43]
	s_cmp_gt_u32 s41, 15
	s_cselect_b32 s0, s1, s0
	s_or_b32 s1, s0, 0x40000000
	v_cmp_le_u32_e64 s[42:43], s1, v7
	s_bcnt1_i32_b64 s41, s[42:43]
	s_cmp_gt_u32 s41, 15
	s_cselect_b32 s0, s1, s0
	s_or_b32 s1, s0, 0x20000000
	v_cmp_le_u32_e64 s[42:43], s1, v7
	s_bcnt1_i32_b64 s41, s[42:43]
	s_cmp_gt_u32 s41, 15
	s_cselect_b32 s0, s1, s0
	s_or_b32 s1, s0, 0x10000000
	v_cmp_le_u32_e64 s[42:43], s1, v7
	s_bcnt1_i32_b64 s41, s[42:43]
	s_cmp_gt_u32 s41, 15
	s_cselect_b32 s0, s1, s0
	s_or_b32 s1, s0, 0x8000000
	v_cmp_le_u32_e64 s[42:43], s1, v7
	s_bcnt1_i32_b64 s41, s[42:43]
	s_cmp_gt_u32 s41, 15
	s_cselect_b32 s0, s1, s0
	s_or_b32 s1, s0, 0x4000000
	v_cmp_le_u32_e64 s[42:43], s1, v7
	s_bcnt1_i32_b64 s41, s[42:43]
	s_cmp_gt_u32 s41, 15
	s_cselect_b32 s0, s1, s0
	s_or_b32 s1, s0, 0x2000000
	v_cmp_le_u32_e64 s[42:43], s1, v7
	s_bcnt1_i32_b64 s41, s[42:43]
	s_cmp_gt_u32 s41, 15
	s_cselect_b32 s0, s1, s0
	s_or_b32 s1, s0, 0x1000000
	v_cmp_le_u32_e64 s[42:43], s1, v7
	s_bcnt1_i32_b64 s41, s[42:43]
	s_cmp_gt_u32 s41, 15
	s_cselect_b32 s0, s1, s0
	s_or_b32 s1, s0, 0x800000
	v_cmp_le_u32_e64 s[42:43], s1, v7
	s_bcnt1_i32_b64 s41, s[42:43]
	s_cmp_gt_u32 s41, 15
	s_cselect_b32 s0, s1, s0
	s_or_b32 s1, s0, 0x400000
	v_cmp_le_u32_e64 s[42:43], s1, v7
	s_bcnt1_i32_b64 s41, s[42:43]
	s_cmp_gt_u32 s41, 15
	s_cselect_b32 s0, s1, s0
	s_or_b32 s1, s0, 0x200000
	v_cmp_le_u32_e64 s[42:43], s1, v7
	s_bcnt1_i32_b64 s41, s[42:43]
	s_cmp_gt_u32 s41, 15
	s_cselect_b32 s0, s1, s0
	s_or_b32 s1, s0, 0x100000
	v_cmp_le_u32_e64 s[42:43], s1, v7
	s_bcnt1_i32_b64 s41, s[42:43]
	s_cmp_gt_u32 s41, 15
	s_cselect_b32 s0, s1, s0
	s_or_b32 s1, s0, 0x80000
	v_cmp_le_u32_e64 s[42:43], s1, v7
	s_bcnt1_i32_b64 s41, s[42:43]
	s_cmp_gt_u32 s41, 15
	s_cselect_b32 s0, s1, s0
	s_or_b32 s1, s0, 0x40000
	v_cmp_le_u32_e64 s[42:43], s1, v7
	s_bcnt1_i32_b64 s41, s[42:43]
	s_cmp_gt_u32 s41, 15
	s_cselect_b32 s0, s1, s0
	s_or_b32 s1, s0, 0x20000
	v_cmp_le_u32_e64 s[42:43], s1, v7
	s_bcnt1_i32_b64 s41, s[42:43]
	s_cmp_gt_u32 s41, 15
	s_cselect_b32 s0, s1, s0
	s_or_b32 s1, s0, 0x10000
	v_cmp_le_u32_e64 s[42:43], s1, v7
	s_bcnt1_i32_b64 s41, s[42:43]
	s_cmp_gt_u32 s41, 15
	s_cselect_b32 s0, s1, s0
	s_or_b32 s1, s0, 0x8000
	v_cmp_le_u32_e64 s[42:43], s1, v7
	s_bcnt1_i32_b64 s41, s[42:43]
	s_cmp_gt_u32 s41, 15
	s_cselect_b32 s0, s1, s0
	s_or_b32 s1, s0, 0x4000
	v_cmp_le_u32_e64 s[42:43], s1, v7
	s_bcnt1_i32_b64 s41, s[42:43]
	s_cmp_gt_u32 s41, 15
	s_cselect_b32 s0, s1, s0
	s_or_b32 s1, s0, 0x2000
	v_cmp_le_u32_e64 s[42:43], s1, v7
	s_bcnt1_i32_b64 s41, s[42:43]
	s_cmp_gt_u32 s41, 15
	s_cselect_b32 s0, s1, s0
	s_or_b32 s1, s0, 0x1000
	v_cmp_le_u32_e64 s[42:43], s1, v7
	s_bcnt1_i32_b64 s41, s[42:43]
	s_cmp_gt_u32 s41, 15
	s_cselect_b32 s0, s1, s0
	s_or_b32 s1, s0, 0x800
	v_cmp_le_u32_e64 s[42:43], s1, v7
	s_bcnt1_i32_b64 s41, s[42:43]
	s_cmp_gt_u32 s41, 15
	s_cselect_b32 s0, s1, s0
	s_or_b32 s1, s0, 0x400
	v_cmp_le_u32_e64 s[42:43], s1, v7
	s_bcnt1_i32_b64 s41, s[42:43]
	s_cmp_gt_u32 s41, 15
	s_cselect_b32 s0, s1, s0
	s_or_b32 s1, s0, 0x200
	v_cmp_le_u32_e64 s[42:43], s1, v7
	s_bcnt1_i32_b64 s41, s[42:43]
	s_cmp_gt_u32 s41, 15
	s_cselect_b32 s0, s1, s0
	s_or_b32 s1, s0, 0x100
	v_cmp_le_u32_e64 s[42:43], s1, v7
	s_bcnt1_i32_b64 s41, s[42:43]
	s_cmp_gt_u32 s41, 15
	s_cselect_b32 s0, s1, s0
	s_or_b32 s1, s0, 0x80
	v_cmp_le_u32_e64 s[42:43], s1, v7
	s_bcnt1_i32_b64 s41, s[42:43]
	s_cmp_gt_u32 s41, 15
	s_cselect_b32 s0, s1, s0
	s_or_b32 s1, s0, 0x40
	v_cmp_le_u32_e64 s[42:43], s1, v7
	s_bcnt1_i32_b64 s41, s[42:43]
	s_cmp_gt_u32 s41, 15
	s_cselect_b32 s0, s1, s0
	s_or_b32 s1, s0, 0x20
	v_cmp_le_u32_e64 s[42:43], s1, v7
	s_bcnt1_i32_b64 s41, s[42:43]
	s_cmp_gt_u32 s41, 15
	s_cselect_b32 s0, s1, s0
	s_or_b32 s1, s0, 0x10
	v_cmp_le_u32_e64 s[42:43], s1, v7
	s_bcnt1_i32_b64 s41, s[42:43]
	s_cmp_gt_u32 s41, 15
	s_cselect_b32 s0, s1, s0
	s_or_b32 s1, s0, 0x8
	v_cmp_le_u32_e64 s[42:43], s1, v7
	s_bcnt1_i32_b64 s41, s[42:43]
	s_cmp_gt_u32 s41, 15
	s_cselect_b32 s0, s1, s0
	s_or_b32 s1, s0, 0x4
	v_cmp_le_u32_e64 s[42:43], s1, v7
	s_bcnt1_i32_b64 s41, s[42:43]
	s_cmp_gt_u32 s41, 15
	s_cselect_b32 s0, s1, s0
	s_or_b32 s1, s0, 0x2
	v_cmp_le_u32_e64 s[42:43], s1, v7
	s_bcnt1_i32_b64 s41, s[42:43]
	s_cmp_gt_u32 s41, 15
	s_cselect_b32 s0, s1, s0
	s_or_b32 s1, s0, 0x1
	v_cmp_le_u32_e64 s[42:43], s1, v7
	s_bcnt1_i32_b64 s41, s[42:43]
	s_cmp_gt_u32 s41, 15
	s_cselect_b32 s0, s1, s0
	v_cmp_le_u32_e32 vcc, s0, v7
	s_and_b64 vcc, s[4:5], vcc
	v_cndmask_b32_e64 v7, 0, 1, vcc
	v_readlane_b32 s0, v6, 0
	s_nop 1
	v_subrev_f32_e32 v6, s0, v6
	v_mul_f32_e32 v6, 0x3fb8aa3b, v6
	v_exp_f32_e32 v6, v6
	v_cmp_ne_u32_e64 s[0:1], 0, v7
	v_cndmask_b32_e32 v6, 0, v6, vcc
	ds_bpermute_b32 v8, v215, v6
	v_mbcnt_lo_u32_b32 v7, s0, 0
	v_mbcnt_hi_u32_b32 v7, s1, v7
	v_cmp_gt_i32_e64 s[0:1], 16, v7
	s_and_b64 s[42:43], vcc, s[0:1]
	s_waitcnt lgkmcnt(0)
	v_add_f32_e32 v8, v6, v8
	ds_bpermute_b32 v9, v214, v8
	s_waitcnt lgkmcnt(0)
	v_add_f32_e32 v8, v8, v9
	ds_bpermute_b32 v9, v216, v8
	s_waitcnt lgkmcnt(0)
	v_add_f32_e32 v8, v8, v9
	ds_bpermute_b32 v9, v217, v8
	s_waitcnt lgkmcnt(0)
	v_add_f32_e32 v8, v8, v9
	ds_bpermute_b32 v9, v218, v8
	s_waitcnt lgkmcnt(0)
	v_add_f32_e32 v8, v8, v9
	ds_bpermute_b32 v9, v219, v8
	s_and_saveexec_b64 s[0:1], s[42:43]
	s_cbranch_execz .LBB0_866
	s_waitcnt lgkmcnt(0)
	v_add_f32_e32 v8, v8, v9
	v_div_scale_f32 v9, s[42:43], v8, v8, v6
	v_rcp_f32_e32 v10, v9
	v_lshlrev_b32_e32 v5, 7, v5
	v_and_b32_e32 v4, 0x7f, v4
	s_movk_i32 s41, 0x3f80
	v_and_or_b32 v4, v5, s41, v4
	v_add_u32_e32 v5, s20, v7
	v_fma_f32 v7, -v9, v10, 1.0
	v_fmac_f32_e32 v10, v7, v10
	v_div_scale_f32 v7, vcc, v6, v8, v6
	v_mul_f32_e32 v11, v7, v10
	v_fma_f32 v12, -v9, v11, v7
	v_fmac_f32_e32 v11, v12, v10
	v_fma_f32 v7, -v9, v11, v7
	v_div_fmas_f32 v7, v7, v10, v11
	v_lshl_add_u32 v5, v5, 2, v131
	v_div_fixup_f32 v6, v7, v8, v6
	ds_write2st64_b32 v5, v4, v6 offset0:12 offset1:14
	s_branch .LBB0_866

	.amdhsa_kernel _Z14fwd_megakernel6Params
		.amdhsa_group_segment_fixed_size 78880
		.amdhsa_private_segment_fixed_size 0
		.amdhsa_kernarg_size 480
		.amdhsa_user_sgpr_count 2
		.amdhsa_user_sgpr_dispatch_ptr 0
		.amdhsa_user_sgpr_queue_ptr 0
		.amdhsa_user_sgpr_kernarg_segment_ptr 1
		.amdhsa_user_sgpr_dispatch_id 0
		.amdhsa_user_sgpr_kernarg_preload_length 0
		.amdhsa_user_sgpr_kernarg_preload_offset 0
		.amdhsa_user_sgpr_private_segment_size 0
		.amdhsa_uses_dynamic_stack 0
		.amdhsa_enable_private_segment 0
		.amdhsa_system_sgpr_workgroup_id_x 1
		.amdhsa_system_sgpr_workgroup_id_y 0
		.amdhsa_system_sgpr_workgroup_id_z 0
		.amdhsa_system_sgpr_workgroup_info 0
		.amdhsa_system_vgpr_workitem_id 2
		.amdhsa_next_free_vgpr 256
		.amdhsa_next_free_sgpr 100
		.amdhsa_accum_offset 256
		.amdhsa_reserve_vcc 1
		.amdhsa_float_round_mode_32 0
		.amdhsa_float_round_mode_16_64 0
		.amdhsa_float_denorm_mode_32 3
		.amdhsa_float_denorm_mode_16_64 3
		.amdhsa_dx10_clamp 1
		.amdhsa_ieee_mode 1
		.amdhsa_fp16_overflow 0
		.amdhsa_tg_split 0
		.amdhsa_exception_fp_ieee_invalid_op 0
		.amdhsa_exception_fp_denorm_src 0
		.amdhsa_exception_fp_ieee_div_zero 0
		.amdhsa_exception_fp_ieee_overflow 0
		.amdhsa_exception_fp_ieee_underflow 0
		.amdhsa_exception_fp_ieee_inexact 0
		.amdhsa_exception_int_div_zero 0
	.end_amdhsa_kernel

amdhsa.kernels:
  - .agpr_count:     0
    .args:
      - .offset:         0
        .size:           224
        .value_kind:     by_value
      - .offset:         224
        .size:           4
        .value_kind:     hidden_block_count_x
      - .offset:         228
        .size:           4
        .value_kind:     hidden_block_count_y
      - .offset:         232
        .size:           4
        .value_kind:     hidden_block_count_z
      - .offset:         236
        .size:           2
        .value_kind:     hidden_group_size_x
      - .offset:         238
        .size:           2
        .value_kind:     hidden_group_size_y
      - .offset:         240
        .size:           2
        .value_kind:     hidden_group_size_z
      - .offset:         242
        .size:           2
        .value_kind:     hidden_remainder_x
      - .offset:         244
        .size:           2
        .value_kind:     hidden_remainder_y
      - .offset:         246
        .size:           2
        .value_kind:     hidden_remainder_z
      - .offset:         264
        .size:           8
        .value_kind:     hidden_global_offset_x
      - .offset:         272
        .size:           8
        .value_kind:     hidden_global_offset_y
      - .offset:         280
        .size:           8
        .value_kind:     hidden_global_offset_z
      - .offset:         288
        .size:           2
        .value_kind:     hidden_grid_dims
      - .offset:         312
        .size:           8
        .value_kind:     hidden_multigrid_sync_arg
    .group_segment_fixed_size: 78880
    .kernarg_segment_align: 8
    .kernarg_segment_size: 480
    .language:       OpenCL C
    .language_version:
      - 2
      - 0
    .max_flat_workgroup_size: 256
    .name:           _Z14fwd_megakernel6Params
    .private_segment_fixed_size: 0
    .sgpr_count:     106
    .sgpr_spill_count: 144
    .symbol:         _Z14fwd_megakernel6Params.kd
    .uniform_work_group_size: 1
    .uses_dynamic_stack: false
    .vgpr_count:     256
    .vgpr_spill_count: 0
    .wavefront_size: 64
